# v006 plus fused-epilogue exchange trimmed: the L1 invalidate after the panel-counter wait is dropped (its only consumers are sc1 loads that bypass L1)
# speedup vs baseline: 1.0063x; 1.0046x over previous
;     __device__ __forceinline__ void xchg(const float (&ss)[2][4], float (&rs)[2][4], const Unit& u, int wr, int wc, int fr, int fq, int tid, int which) const {
;     ...
;         if (tid < 64) { const unsigned want = target0 + 16u * (unsigned)which; unsigned spins = 0;
;             while ((unsigned)__builtin_amdgcn_readfirstlane(__hip_atomic_load(c, __ATOMIC_RELAXED, __HIP_MEMORY_SCOPE_AGENT)) < want) { __builtin_amdgcn_s_sleep(1); if (++spins > (1u << 20)) break; }
;             __builtin_amdgcn_fence(__ATOMIC_ACQUIRE, "agent"); }
;         asm volatile("s_waitcnt vmcnt(0) lgkmcnt(0)" ::: "memory"); __builtin_amdgcn_s_barrier(); asm volatile("" ::: "memory");
.LBB0_1068:
	s_waitcnt lgkmcnt(0)
	s_nop 0
